# +E17 P1 sigmoid epilogue: the 8 sigmoid chains of each 16-byte store group get their own temps and are issued level by level (was one serial temp); wait states re-derived
# baseline (speedup 1.0000x reference)
; __device__ __forceinline__ unsigned cvt_pk_bf16(float lo, float hi) { const f32x2 v = {lo, hi}; return __builtin_bit_cast(unsigned, __builtin_convertvector(v, bf16x2_t)); }
; __device__ __forceinline__ float sigmoidf_(float x) { return __builtin_amdgcn_rcpf(1.0f + __builtin_amdgcn_exp2f(-1.4426950408889634f * x)); }
; __device__ __forceinline__ float siluf_(float x) { return x * sigmoidf_(x); }
; template <int ACT> __device__ __forceinline__ void epi_store_bf16(const f32x4 (&acc)[2][2][4][2], const float (&rs)[2][4], bf16_t* out, int ldo, int row0, int col0) {
;     ...
;         for (int m = 0; m < 4; ++m) { bf16_t* rowp = out + (size_t)(row0 + ai * 128 + m * 16) * ldo + col0; const float s = rs[ai][m];
; #pragma unroll
;             for (int bj = 0; bj < 2; ++bj) { const f32x4 v0 = acc[ai][bj][m][0] * s, v1 = acc[ai][bj][m][1] * s;
;                 u32x4 w; w.x = cvt_pk_bf16(act_apply<ACT>(v0[0]), act_apply<ACT>(v0[1])); w.y = cvt_pk_bf16(act_apply<ACT>(v0[2]), act_apply<ACT>(v0[3]));
;                 w.z = cvt_pk_bf16(act_apply<ACT>(v1[0]), act_apply<ACT>(v1[1])); w.w = cvt_pk_bf16(act_apply<ACT>(v1[2]), act_apply<ACT>(v1[3]));
;                 *(u32x4*)(rowp + bj * 128) = w; } }
.LBB0_210:
	s_andn2_b64 vcc, exec, s[24:25]
	s_cbranch_vccnz .LBB0_212
	v_ashrrev_i32_e32 v169, 31, v168
	s_waitcnt lgkmcnt(0)
	v_pk_mul_f32 v[174:175], v[128:129], v[170:171] op_sel_hi:[1,0]
	v_lshlrev_b64 v[132:133], 15, v[168:169]
	v_pk_mul_f32 v[176:177], v[130:131], v[170:171] op_sel_hi:[1,0]
	v_pk_mul_f32 v[180:181], v[124:125], v[170:171] op_sel_hi:[1,0]
	v_pk_mul_f32 v[178:179], v[126:127], v[170:171] op_sel_hi:[1,0]
	v_ashrrev_i32_e32 v173, 31, v172
	s_mov_b32 s15, 0x400000
	s_mov_b64 s[22:23], 0x400000
	v_mul_f32_e32 v214, 0xbfb8aa3b, v174
	v_mul_f32_e32 v215, 0xbfb8aa3b, v175
	v_lshl_add_u64 v[134:135], v[172:173], 1, s[62:63]
	v_mul_f32_e32 v216, 0xbfb8aa3b, v176
	v_mul_f32_e32 v217, 0xbfb8aa3b, v177
	v_mul_f32_e32 v218, 0xbfb8aa3b, v180
	v_mul_f32_e32 v219, 0xbfb8aa3b, v181
	v_mul_f32_e32 v220, 0xbfb8aa3b, v178
	v_mul_f32_e32 v221, 0xbfb8aa3b, v179
	v_exp_f32_e32 v214, v214
	v_exp_f32_e32 v215, v215
	v_lshl_add_u64 v[132:133], v[134:135], 0, v[132:133]
	v_exp_f32_e32 v216, v216
	v_exp_f32_e32 v217, v217
	v_exp_f32_e32 v218, v218
	v_exp_f32_e32 v219, v219
	v_exp_f32_e32 v220, v220
	v_exp_f32_e32 v221, v221
	v_add_f32_e32 v214, 1.0, v214
	v_add_f32_e32 v215, 1.0, v215
	v_add_f32_e32 v216, 1.0, v216
	v_add_f32_e32 v217, 1.0, v217
	v_add_f32_e32 v218, 1.0, v218
	v_add_f32_e32 v219, 1.0, v219
	v_add_f32_e32 v220, 1.0, v220
	v_add_f32_e32 v221, 1.0, v221
	v_rcp_f32_e32 v222, v214
	v_rcp_f32_e32 v223, v215
	v_rcp_f32_e32 v224, v216
	v_rcp_f32_e32 v225, v217
	v_rcp_f32_e32 v226, v218
	v_rcp_f32_e32 v227, v219
	v_rcp_f32_e32 v228, v220
	v_rcp_f32_e32 v229, v221
	v_pk_mul_f32 v[174:175], v[174:175], v[222:223]
	v_pk_mul_f32 v[176:177], v[176:177], v[224:225]
	v_pk_mul_f32 v[178:179], v[178:179], v[228:229]
	v_cvt_pk_bf16_f32 v174, v174, v175
	v_cvt_pk_bf16_f32 v175, v176, v177
	v_pk_mul_f32 v[176:177], v[180:181], v[226:227]
	v_cvt_pk_bf16_f32 v176, v176, v177
	v_cvt_pk_bf16_f32 v177, v178, v179
	global_store_dwordx4 v[132:133], v[174:177], off
	v_pk_mul_f32 v[180:181], v[116:117], v[170:171] op_sel_hi:[1,0]
	v_pk_mul_f32 v[178:179], v[118:119], v[170:171] op_sel_hi:[1,0]
	v_pk_mul_f32 v[174:175], v[120:121], v[170:171] op_sel_hi:[1,0]
	v_pk_mul_f32 v[176:177], v[122:123], v[170:171] op_sel_hi:[1,0]
	v_mul_f32_e32 v214, 0xbfb8aa3b, v174
	v_mul_f32_e32 v215, 0xbfb8aa3b, v175
	v_mul_f32_e32 v216, 0xbfb8aa3b, v176
	v_mul_f32_e32 v217, 0xbfb8aa3b, v177
	v_mul_f32_e32 v218, 0xbfb8aa3b, v180
	v_mul_f32_e32 v219, 0xbfb8aa3b, v181
	v_mul_f32_e32 v220, 0xbfb8aa3b, v178
	v_mul_f32_e32 v221, 0xbfb8aa3b, v179
	v_exp_f32_e32 v214, v214
	v_exp_f32_e32 v215, v215
	v_exp_f32_e32 v216, v216
	v_exp_f32_e32 v217, v217
	v_exp_f32_e32 v218, v218
	v_exp_f32_e32 v219, v219
	v_exp_f32_e32 v220, v220
	v_exp_f32_e32 v221, v221
	v_add_f32_e32 v214, 1.0, v214
	v_add_f32_e32 v215, 1.0, v215
	v_add_f32_e32 v216, 1.0, v216
	v_add_f32_e32 v217, 1.0, v217
	v_add_f32_e32 v218, 1.0, v218
	v_add_f32_e32 v219, 1.0, v219
	v_add_f32_e32 v220, 1.0, v220
	v_add_f32_e32 v221, 1.0, v221
	v_rcp_f32_e32 v222, v214
	v_rcp_f32_e32 v223, v215
	v_rcp_f32_e32 v224, v216
	v_rcp_f32_e32 v225, v217
	v_rcp_f32_e32 v226, v218
	v_rcp_f32_e32 v227, v219
	v_rcp_f32_e32 v228, v220
	v_rcp_f32_e32 v229, v221
	v_pk_mul_f32 v[174:175], v[174:175], v[222:223]
	v_pk_mul_f32 v[176:177], v[176:177], v[224:225]
	v_pk_mul_f32 v[178:179], v[178:179], v[228:229]
	v_cvt_pk_bf16_f32 v174, v174, v175
	v_cvt_pk_bf16_f32 v175, v176, v177
	v_pk_mul_f32 v[176:177], v[180:181], v[226:227]
	v_cvt_pk_bf16_f32 v176, v176, v177
	v_mov_b32_e32 v180, v171
	v_cvt_pk_bf16_f32 v177, v178, v179
	global_store_dwordx4 v[132:133], v[174:177], off offset:256
	v_pk_mul_f32 v[178:179], v[114:115], v[180:181] op_sel_hi:[1,0]
	v_pk_mul_f32 v[184:185], v[108:109], v[180:181] op_sel_hi:[1,0]
	v_pk_mul_f32 v[176:177], v[112:113], v[180:181] op_sel_hi:[1,0]
	v_pk_mul_f32 v[182:183], v[110:111], v[180:181] op_sel_hi:[1,0]
	v_or_b32_e32 v174, 16, v168
	v_mul_f32_e32 v214, 0xbfb8aa3b, v176
	v_ashrrev_i32_e32 v175, 31, v174
	v_mul_f32_e32 v215, 0xbfb8aa3b, v177
	v_mul_f32_e32 v216, 0xbfb8aa3b, v178
	v_mul_f32_e32 v217, 0xbfb8aa3b, v179
	v_mul_f32_e32 v218, 0xbfb8aa3b, v184
	v_mul_f32_e32 v219, 0xbfb8aa3b, v185
	v_mul_f32_e32 v220, 0xbfb8aa3b, v182
	v_mul_f32_e32 v221, 0xbfb8aa3b, v183
	v_exp_f32_e32 v214, v214
	v_lshlrev_b64 v[174:175], 15, v[174:175]
	v_exp_f32_e32 v215, v215
	v_exp_f32_e32 v216, v216
	v_exp_f32_e32 v217, v217
	v_exp_f32_e32 v218, v218
	v_exp_f32_e32 v219, v219
	v_exp_f32_e32 v220, v220
	v_exp_f32_e32 v221, v221
	v_add_f32_e32 v214, 1.0, v214
	v_lshl_add_u64 v[174:175], v[134:135], 0, v[174:175]
	v_add_f32_e32 v215, 1.0, v215
	v_add_f32_e32 v216, 1.0, v216
	v_add_f32_e32 v217, 1.0, v217
	v_add_f32_e32 v218, 1.0, v218
	v_add_f32_e32 v219, 1.0, v219
	v_add_f32_e32 v220, 1.0, v220
	v_add_f32_e32 v221, 1.0, v221
	v_rcp_f32_e32 v222, v214
	v_rcp_f32_e32 v223, v215
	v_rcp_f32_e32 v224, v216
	v_rcp_f32_e32 v225, v217
	v_rcp_f32_e32 v226, v218
	v_rcp_f32_e32 v227, v219
	v_rcp_f32_e32 v228, v220
	v_rcp_f32_e32 v229, v221
	v_pk_mul_f32 v[176:177], v[176:177], v[222:223]
	v_pk_mul_f32 v[178:179], v[178:179], v[224:225]
	v_pk_mul_f32 v[182:183], v[182:183], v[228:229]
	v_cvt_pk_bf16_f32 v176, v176, v177
	v_cvt_pk_bf16_f32 v177, v178, v179
	v_pk_mul_f32 v[178:179], v[184:185], v[226:227]
	v_cvt_pk_bf16_f32 v178, v178, v179
	v_cvt_pk_bf16_f32 v179, v182, v183
	global_store_dwordx4 v[174:175], v[176:179], off
	v_pk_mul_f32 v[182:183], v[102:103], v[180:181] op_sel_hi:[1,0]
	s_nop 0
	v_pk_mul_f32 v[176:177], v[104:105], v[180:181] op_sel_hi:[1,0]
	v_pk_mul_f32 v[178:179], v[106:107], v[180:181] op_sel_hi:[1,0]
	v_mul_f32_e32 v214, 0xbfb8aa3b, v176
; __device__ __forceinline__ unsigned cvt_pk_bf16(float lo, float hi) { const f32x2 v = {lo, hi}; return __builtin_bit_cast(unsigned, __builtin_convertvector(v, bf16x2_t)); }
; __device__ __forceinline__ float sigmoidf_(float x) { return __builtin_amdgcn_rcpf(1.0f + __builtin_amdgcn_exp2f(-1.4426950408889634f * x)); }
; __device__ __forceinline__ float siluf_(float x) { return x * sigmoidf_(x); }
; template <int ACT> __device__ __forceinline__ void epi_store_bf16(const f32x4 (&acc)[2][2][4][2], const float (&rs)[2][4], bf16_t* out, int ldo, int row0, int col0) {
;     ...
;         for (int m = 0; m < 4; ++m) { bf16_t* rowp = out + (size_t)(row0 + ai * 128 + m * 16) * ldo + col0; const float s = rs[ai][m];
; #pragma unroll
;             for (int bj = 0; bj < 2; ++bj) { const f32x4 v0 = acc[ai][bj][m][0] * s, v1 = acc[ai][bj][m][1] * s;
;                 u32x4 w; w.x = cvt_pk_bf16(act_apply<ACT>(v0[0]), act_apply<ACT>(v0[1])); w.y = cvt_pk_bf16(act_apply<ACT>(v0[2]), act_apply<ACT>(v0[3]));
;                 w.z = cvt_pk_bf16(act_apply<ACT>(v1[0]), act_apply<ACT>(v1[1])); w.w = cvt_pk_bf16(act_apply<ACT>(v1[2]), act_apply<ACT>(v1[3]));
;                 *(u32x4*)(rowp + bj * 128) = w; } }
	v_pk_mul_f32 v[180:181], v[100:101], v[180:181] op_sel_hi:[1,0]
	v_mul_f32_e32 v215, 0xbfb8aa3b, v177
	v_mul_f32_e32 v216, 0xbfb8aa3b, v178
	v_mul_f32_e32 v217, 0xbfb8aa3b, v179
	v_mul_f32_e32 v220, 0xbfb8aa3b, v182
	v_mul_f32_e32 v221, 0xbfb8aa3b, v183
	v_exp_f32_e32 v214, v214
	v_exp_f32_e32 v215, v215
	v_exp_f32_e32 v216, v216
	v_exp_f32_e32 v217, v217
	v_mul_f32_e32 v218, 0xbfb8aa3b, v180
	v_mul_f32_e32 v219, 0xbfb8aa3b, v181
	v_exp_f32_e32 v220, v220
	v_exp_f32_e32 v221, v221
	v_add_f32_e32 v214, 1.0, v214
	v_add_f32_e32 v215, 1.0, v215
	v_add_f32_e32 v216, 1.0, v216
	v_add_f32_e32 v217, 1.0, v217
	v_exp_f32_e32 v218, v218
	v_exp_f32_e32 v219, v219
	v_add_f32_e32 v220, 1.0, v220
	v_add_f32_e32 v221, 1.0, v221
	v_rcp_f32_e32 v222, v214
	v_rcp_f32_e32 v223, v215
	v_rcp_f32_e32 v224, v216
	v_rcp_f32_e32 v225, v217
	v_add_f32_e32 v218, 1.0, v218
	v_add_f32_e32 v219, 1.0, v219
	v_rcp_f32_e32 v228, v220
	v_rcp_f32_e32 v229, v221
	v_pk_mul_f32 v[176:177], v[176:177], v[222:223]
	v_pk_mul_f32 v[178:179], v[178:179], v[224:225]
	v_rcp_f32_e32 v226, v218
	v_rcp_f32_e32 v227, v219
	v_cvt_pk_bf16_f32 v176, v176, v177
	v_cvt_pk_bf16_f32 v177, v178, v179
	v_pk_mul_f32 v[178:179], v[180:181], v[226:227]
	v_cvt_pk_bf16_f32 v178, v178, v179
	v_pk_mul_f32 v[180:181], v[182:183], v[228:229]
	v_cvt_pk_bf16_f32 v179, v180, v181
	global_store_dwordx4 v[174:175], v[176:179], off offset:256
	v_pk_mul_f32 v[182:183], v[92:93], v[166:167] op_sel_hi:[1,0]
	v_pk_mul_f32 v[180:181], v[94:95], v[166:167] op_sel_hi:[1,0]
	v_pk_mul_f32 v[176:177], v[96:97], v[166:167] op_sel_hi:[1,0]
	v_pk_mul_f32 v[178:179], v[98:99], v[166:167] op_sel_hi:[1,0]
	v_or_b32_e32 v174, 32, v168
	v_mul_f32_e32 v214, 0xbfb8aa3b, v176
	v_ashrrev_i32_e32 v175, 31, v174
	v_mul_f32_e32 v215, 0xbfb8aa3b, v177
	v_mul_f32_e32 v216, 0xbfb8aa3b, v178
	v_mul_f32_e32 v217, 0xbfb8aa3b, v179
	v_mul_f32_e32 v218, 0xbfb8aa3b, v182
	v_mul_f32_e32 v219, 0xbfb8aa3b, v183
	v_mul_f32_e32 v220, 0xbfb8aa3b, v180
	v_mul_f32_e32 v221, 0xbfb8aa3b, v181
	v_exp_f32_e32 v214, v214
	v_lshlrev_b64 v[174:175], 15, v[174:175]
	v_exp_f32_e32 v215, v215
	v_exp_f32_e32 v216, v216
	v_exp_f32_e32 v217, v217
	v_exp_f32_e32 v218, v218
	v_exp_f32_e32 v219, v219
	v_exp_f32_e32 v220, v220
	v_exp_f32_e32 v221, v221
	v_add_f32_e32 v214, 1.0, v214
	v_lshl_add_u64 v[174:175], v[134:135], 0, v[174:175]
	v_add_f32_e32 v215, 1.0, v215
	v_add_f32_e32 v216, 1.0, v216
	v_add_f32_e32 v217, 1.0, v217
	v_add_f32_e32 v218, 1.0, v218
	v_add_f32_e32 v219, 1.0, v219
	v_add_f32_e32 v220, 1.0, v220
	v_add_f32_e32 v221, 1.0, v221
	v_rcp_f32_e32 v222, v214
	v_rcp_f32_e32 v223, v215
	v_rcp_f32_e32 v224, v216
	v_rcp_f32_e32 v225, v217
	v_rcp_f32_e32 v226, v218
	v_rcp_f32_e32 v227, v219
	v_rcp_f32_e32 v228, v220
	v_rcp_f32_e32 v229, v221
	v_pk_mul_f32 v[176:177], v[176:177], v[222:223]
	v_pk_mul_f32 v[178:179], v[178:179], v[224:225]
	v_pk_mul_f32 v[180:181], v[180:181], v[228:229]
	v_cvt_pk_bf16_f32 v176, v176, v177
	v_cvt_pk_bf16_f32 v177, v178, v179
	v_pk_mul_f32 v[178:179], v[182:183], v[226:227]
	v_cvt_pk_bf16_f32 v178, v178, v179
	v_cvt_pk_bf16_f32 v179, v180, v181
	global_store_dwordx4 v[174:175], v[176:179], off
	v_pk_mul_f32 v[182:183], v[84:85], v[166:167] op_sel_hi:[1,0]
	v_pk_mul_f32 v[180:181], v[86:87], v[166:167] op_sel_hi:[1,0]
	v_pk_mul_f32 v[176:177], v[88:89], v[166:167] op_sel_hi:[1,0]
	v_pk_mul_f32 v[178:179], v[90:91], v[166:167] op_sel_hi:[1,0]
	v_mul_f32_e32 v214, 0xbfb8aa3b, v176
	v_mul_f32_e32 v215, 0xbfb8aa3b, v177
	v_mul_f32_e32 v216, 0xbfb8aa3b, v178
	v_mul_f32_e32 v217, 0xbfb8aa3b, v179
	v_mul_f32_e32 v218, 0xbfb8aa3b, v182
	v_mul_f32_e32 v219, 0xbfb8aa3b, v183
	v_mul_f32_e32 v220, 0xbfb8aa3b, v180
	v_mul_f32_e32 v221, 0xbfb8aa3b, v181
	v_exp_f32_e32 v214, v214
	v_exp_f32_e32 v215, v215
	v_exp_f32_e32 v216, v216
	v_exp_f32_e32 v217, v217
	v_exp_f32_e32 v218, v218
	v_exp_f32_e32 v219, v219
	v_exp_f32_e32 v220, v220
	v_exp_f32_e32 v221, v221
	v_add_f32_e32 v214, 1.0, v214
	v_add_f32_e32 v215, 1.0, v215
	v_add_f32_e32 v216, 1.0, v216
	v_add_f32_e32 v217, 1.0, v217
	v_add_f32_e32 v218, 1.0, v218
	v_add_f32_e32 v219, 1.0, v219
	v_add_f32_e32 v220, 1.0, v220
	v_add_f32_e32 v221, 1.0, v221
	v_rcp_f32_e32 v222, v214
	v_rcp_f32_e32 v223, v215
	v_rcp_f32_e32 v224, v216
	v_rcp_f32_e32 v225, v217
	v_rcp_f32_e32 v226, v218
	v_rcp_f32_e32 v227, v219
	v_rcp_f32_e32 v228, v220
	v_rcp_f32_e32 v229, v221
	v_pk_mul_f32 v[176:177], v[176:177], v[222:223]
	v_pk_mul_f32 v[178:179], v[178:179], v[224:225]
	v_pk_mul_f32 v[180:181], v[180:181], v[228:229]
	v_cvt_pk_bf16_f32 v176, v176, v177
	v_cvt_pk_bf16_f32 v177, v178, v179
	v_pk_mul_f32 v[178:179], v[182:183], v[226:227]
	v_cvt_pk_bf16_f32 v178, v178, v179
	v_cvt_pk_bf16_f32 v179, v180, v181
	global_store_dwordx4 v[174:175], v[176:179], off offset:256
	s_nop 1
	v_or_b32_e32 v174, 48, v168
	v_mov_b32_e32 v178, v167
	v_ashrrev_i32_e32 v175, 31, v174
	v_pk_mul_f32 v[176:177], v[82:83], v[178:179] op_sel_hi:[1,0]
	v_pk_mul_f32 v[182:183], v[76:77], v[178:179] op_sel_hi:[1,0]
	v_pk_mul_f32 v[180:181], v[78:79], v[178:179] op_sel_hi:[1,0]
	v_lshlrev_b64 v[174:175], 15, v[174:175]
	v_mul_f32_e32 v216, 0xbfb8aa3b, v176
	v_mul_f32_e32 v217, 0xbfb8aa3b, v177
	v_mul_f32_e32 v218, 0xbfb8aa3b, v182
	v_mul_f32_e32 v219, 0xbfb8aa3b, v183
	v_mul_f32_e32 v220, 0xbfb8aa3b, v180
	v_mul_f32_e32 v221, 0xbfb8aa3b, v181
	v_lshl_add_u64 v[134:135], v[134:135], 0, v[174:175]
	v_exp_f32_e32 v216, v216
	v_exp_f32_e32 v217, v217
	v_exp_f32_e32 v218, v218
	v_exp_f32_e32 v219, v219
	v_exp_f32_e32 v220, v220
	v_exp_f32_e32 v221, v221
	v_pk_mul_f32 v[174:175], v[80:81], v[178:179] op_sel_hi:[1,0]
	v_add_f32_e32 v216, 1.0, v216
; __device__ __forceinline__ unsigned cvt_pk_bf16(float lo, float hi) { const f32x2 v = {lo, hi}; return __builtin_bit_cast(unsigned, __builtin_convertvector(v, bf16x2_t)); }
; __device__ __forceinline__ float sigmoidf_(float x) { return __builtin_amdgcn_rcpf(1.0f + __builtin_amdgcn_exp2f(-1.4426950408889634f * x)); }
; __device__ __forceinline__ float siluf_(float x) { return x * sigmoidf_(x); }
; template <int ACT> __device__ __forceinline__ void epi_store_bf16(const f32x4 (&acc)[2][2][4][2], const float (&rs)[2][4], bf16_t* out, int ldo, int row0, int col0) {
;     ...
;         for (int m = 0; m < 4; ++m) { bf16_t* rowp = out + (size_t)(row0 + ai * 128 + m * 16) * ldo + col0; const float s = rs[ai][m];
; #pragma unroll
;             for (int bj = 0; bj < 2; ++bj) { const f32x4 v0 = acc[ai][bj][m][0] * s, v1 = acc[ai][bj][m][1] * s;
;                 u32x4 w; w.x = cvt_pk_bf16(act_apply<ACT>(v0[0]), act_apply<ACT>(v0[1])); w.y = cvt_pk_bf16(act_apply<ACT>(v0[2]), act_apply<ACT>(v0[3]));
;                 w.z = cvt_pk_bf16(act_apply<ACT>(v1[0]), act_apply<ACT>(v1[1])); w.w = cvt_pk_bf16(act_apply<ACT>(v1[2]), act_apply<ACT>(v1[3]));
;                 *(u32x4*)(rowp + bj * 128) = w; } }
	v_add_f32_e32 v217, 1.0, v217
	v_add_f32_e32 v218, 1.0, v218
	v_add_f32_e32 v219, 1.0, v219
	v_add_f32_e32 v220, 1.0, v220
	v_add_f32_e32 v221, 1.0, v221
	v_mul_f32_e32 v214, 0xbfb8aa3b, v174
	v_mul_f32_e32 v215, 0xbfb8aa3b, v175
	v_rcp_f32_e32 v224, v216
	v_rcp_f32_e32 v225, v217
	v_rcp_f32_e32 v226, v218
	v_rcp_f32_e32 v227, v219
	v_rcp_f32_e32 v228, v220
	v_rcp_f32_e32 v229, v221
	v_exp_f32_e32 v214, v214
	v_exp_f32_e32 v215, v215
	v_pk_mul_f32 v[176:177], v[176:177], v[224:225]
	v_pk_mul_f32 v[180:181], v[180:181], v[228:229]
	v_add_f32_e32 v214, 1.0, v214
	v_add_f32_e32 v215, 1.0, v215
	v_rcp_f32_e32 v222, v214
	v_rcp_f32_e32 v223, v215
	s_nop 0
	v_pk_mul_f32 v[174:175], v[174:175], v[222:223]
	v_cvt_pk_bf16_f32 v174, v174, v175
	v_cvt_pk_bf16_f32 v175, v176, v177
	v_pk_mul_f32 v[176:177], v[182:183], v[226:227]
	v_cvt_pk_bf16_f32 v176, v176, v177
	v_cvt_pk_bf16_f32 v177, v180, v181
	global_store_dwordx4 v[134:135], v[174:177], off
	v_pk_mul_f32 v[180:181], v[70:71], v[178:179] op_sel_hi:[1,0]
	s_nop 0
	v_pk_mul_f32 v[174:175], v[72:73], v[178:179] op_sel_hi:[1,0]
	v_pk_mul_f32 v[176:177], v[74:75], v[178:179] op_sel_hi:[1,0]
	v_mul_f32_e32 v214, 0xbfb8aa3b, v174
	v_pk_mul_f32 v[178:179], v[68:69], v[178:179] op_sel_hi:[1,0]
	v_mul_f32_e32 v215, 0xbfb8aa3b, v175
	v_mul_f32_e32 v216, 0xbfb8aa3b, v176
	v_mul_f32_e32 v217, 0xbfb8aa3b, v177
	v_mul_f32_e32 v220, 0xbfb8aa3b, v180
	v_mul_f32_e32 v221, 0xbfb8aa3b, v181
	v_exp_f32_e32 v214, v214
	v_exp_f32_e32 v215, v215
	v_exp_f32_e32 v216, v216
	v_exp_f32_e32 v217, v217
	v_mul_f32_e32 v218, 0xbfb8aa3b, v178
	v_mul_f32_e32 v219, 0xbfb8aa3b, v179
	v_exp_f32_e32 v220, v220
	v_exp_f32_e32 v221, v221
	v_add_f32_e32 v214, 1.0, v214
	v_add_f32_e32 v215, 1.0, v215
	v_add_f32_e32 v216, 1.0, v216
	v_add_f32_e32 v217, 1.0, v217
	v_exp_f32_e32 v218, v218
	v_exp_f32_e32 v219, v219
	v_add_f32_e32 v220, 1.0, v220
	v_add_f32_e32 v221, 1.0, v221
	v_rcp_f32_e32 v222, v214
	v_rcp_f32_e32 v223, v215
	v_rcp_f32_e32 v224, v216
	v_rcp_f32_e32 v225, v217
	v_add_f32_e32 v218, 1.0, v218
	v_add_f32_e32 v219, 1.0, v219
	v_rcp_f32_e32 v228, v220
	v_rcp_f32_e32 v229, v221
	v_pk_mul_f32 v[174:175], v[174:175], v[222:223]
	v_pk_mul_f32 v[176:177], v[176:177], v[224:225]
	v_rcp_f32_e32 v226, v218
	v_rcp_f32_e32 v227, v219
	v_cvt_pk_bf16_f32 v174, v174, v175
	v_cvt_pk_bf16_f32 v175, v176, v177
	v_pk_mul_f32 v[176:177], v[178:179], v[226:227]
	v_cvt_pk_bf16_f32 v176, v176, v177
	v_pk_mul_f32 v[178:179], v[180:181], v[228:229]
	v_cvt_pk_bf16_f32 v177, v178, v179
	global_store_dwordx4 v[134:135], v[174:177], off offset:256
	v_pk_mul_f32 v[180:181], v[60:61], v[164:165] op_sel_hi:[1,0]
	v_pk_mul_f32 v[178:179], v[62:63], v[164:165] op_sel_hi:[1,0]
	v_pk_mul_f32 v[174:175], v[64:65], v[164:165] op_sel_hi:[1,0]
	v_pk_mul_f32 v[176:177], v[66:67], v[164:165] op_sel_hi:[1,0]
	v_lshl_add_u64 v[134:135], v[132:133], 0, s[22:23]
	v_mul_f32_e32 v214, 0xbfb8aa3b, v174
	s_mov_b64 s[22:23], 0x480000
	v_mul_f32_e32 v215, 0xbfb8aa3b, v175
	v_mul_f32_e32 v216, 0xbfb8aa3b, v176
	v_mul_f32_e32 v217, 0xbfb8aa3b, v177
	v_mul_f32_e32 v218, 0xbfb8aa3b, v180
	v_mul_f32_e32 v219, 0xbfb8aa3b, v181
	v_mul_f32_e32 v220, 0xbfb8aa3b, v178
	v_mul_f32_e32 v221, 0xbfb8aa3b, v179
	v_exp_f32_e32 v214, v214
	v_exp_f32_e32 v215, v215
	v_exp_f32_e32 v216, v216
	v_exp_f32_e32 v217, v217
	v_exp_f32_e32 v218, v218
	v_exp_f32_e32 v219, v219
	v_exp_f32_e32 v220, v220
	v_exp_f32_e32 v221, v221
	v_add_f32_e32 v214, 1.0, v214
	v_add_f32_e32 v215, 1.0, v215
	v_add_f32_e32 v216, 1.0, v216
	v_add_f32_e32 v217, 1.0, v217
	v_add_f32_e32 v218, 1.0, v218
	v_add_f32_e32 v219, 1.0, v219
	v_add_f32_e32 v220, 1.0, v220
	v_add_f32_e32 v221, 1.0, v221
	v_rcp_f32_e32 v222, v214
	v_rcp_f32_e32 v223, v215
	v_rcp_f32_e32 v224, v216
	v_rcp_f32_e32 v225, v217
	v_rcp_f32_e32 v226, v218
	v_rcp_f32_e32 v227, v219
	v_rcp_f32_e32 v228, v220
	v_rcp_f32_e32 v229, v221
	v_pk_mul_f32 v[174:175], v[174:175], v[222:223]
	v_pk_mul_f32 v[176:177], v[176:177], v[224:225]
	v_pk_mul_f32 v[178:179], v[178:179], v[228:229]
	v_cvt_pk_bf16_f32 v174, v174, v175
	v_cvt_pk_bf16_f32 v175, v176, v177
	v_pk_mul_f32 v[176:177], v[180:181], v[226:227]
	v_cvt_pk_bf16_f32 v176, v176, v177
	v_pk_mul_f32 v[180:181], v[52:53], v[164:165] op_sel_hi:[1,0]
	v_cvt_pk_bf16_f32 v177, v178, v179
	v_add_co_u32_e32 v178, vcc, s15, v132
	s_nop 1
	v_addc_co_u32_e32 v179, vcc, 0, v133, vcc
	global_store_dwordx4 v[178:179], v[174:177], off
	s_nop 1
	v_pk_mul_f32 v[178:179], v[54:55], v[164:165] op_sel_hi:[1,0]
	s_mov_b32 s15, 0x480000
	v_pk_mul_f32 v[174:175], v[56:57], v[164:165] op_sel_hi:[1,0]
	v_pk_mul_f32 v[176:177], v[58:59], v[164:165] op_sel_hi:[1,0]
	v_mul_f32_e32 v218, 0xbfb8aa3b, v180
	v_mul_f32_e32 v219, 0xbfb8aa3b, v181
	v_mul_f32_e32 v214, 0xbfb8aa3b, v174
	v_mul_f32_e32 v215, 0xbfb8aa3b, v175
	v_mul_f32_e32 v216, 0xbfb8aa3b, v176
	v_mul_f32_e32 v217, 0xbfb8aa3b, v177
	v_exp_f32_e32 v218, v218
	v_exp_f32_e32 v219, v219
	v_mul_f32_e32 v220, 0xbfb8aa3b, v178
	v_mul_f32_e32 v221, 0xbfb8aa3b, v179
	v_exp_f32_e32 v214, v214
	v_exp_f32_e32 v215, v215
	v_exp_f32_e32 v216, v216
	v_exp_f32_e32 v217, v217
	v_add_f32_e32 v218, 1.0, v218
	v_add_f32_e32 v219, 1.0, v219
	v_exp_f32_e32 v220, v220
	v_exp_f32_e32 v221, v221
	v_add_f32_e32 v214, 1.0, v214
	v_add_f32_e32 v215, 1.0, v215
	v_add_f32_e32 v216, 1.0, v216
	v_add_f32_e32 v217, 1.0, v217
	v_rcp_f32_e32 v226, v218
	v_rcp_f32_e32 v227, v219
	v_add_f32_e32 v220, 1.0, v220
	v_add_f32_e32 v221, 1.0, v221
	v_rcp_f32_e32 v222, v214
	v_rcp_f32_e32 v223, v215
	v_rcp_f32_e32 v224, v216
	v_rcp_f32_e32 v225, v217
	v_rcp_f32_e32 v228, v220
	v_rcp_f32_e32 v229, v221
; __device__ __forceinline__ unsigned cvt_pk_bf16(float lo, float hi) { const f32x2 v = {lo, hi}; return __builtin_bit_cast(unsigned, __builtin_convertvector(v, bf16x2_t)); }
; __device__ __forceinline__ float sigmoidf_(float x) { return __builtin_amdgcn_rcpf(1.0f + __builtin_amdgcn_exp2f(-1.4426950408889634f * x)); }
; __device__ __forceinline__ float siluf_(float x) { return x * sigmoidf_(x); }
; template <int ACT> __device__ __forceinline__ void epi_store_bf16(const f32x4 (&acc)[2][2][4][2], const float (&rs)[2][4], bf16_t* out, int ldo, int row0, int col0) {
;     ...
;         for (int m = 0; m < 4; ++m) { bf16_t* rowp = out + (size_t)(row0 + ai * 128 + m * 16) * ldo + col0; const float s = rs[ai][m];
; #pragma unroll
;             for (int bj = 0; bj < 2; ++bj) { const f32x4 v0 = acc[ai][bj][m][0] * s, v1 = acc[ai][bj][m][1] * s;
;                 u32x4 w; w.x = cvt_pk_bf16(act_apply<ACT>(v0[0]), act_apply<ACT>(v0[1])); w.y = cvt_pk_bf16(act_apply<ACT>(v0[2]), act_apply<ACT>(v0[3]));
;                 w.z = cvt_pk_bf16(act_apply<ACT>(v1[0]), act_apply<ACT>(v1[1])); w.w = cvt_pk_bf16(act_apply<ACT>(v1[2]), act_apply<ACT>(v1[3]));
;                 *(u32x4*)(rowp + bj * 128) = w; } }
	v_pk_mul_f32 v[174:175], v[174:175], v[222:223]
	v_pk_mul_f32 v[176:177], v[176:177], v[224:225]
	v_pk_mul_f32 v[178:179], v[178:179], v[228:229]
	v_cvt_pk_bf16_f32 v174, v174, v175
	v_cvt_pk_bf16_f32 v175, v176, v177
	v_pk_mul_f32 v[176:177], v[180:181], v[226:227]
	v_cvt_pk_bf16_f32 v176, v176, v177
	v_cvt_pk_bf16_f32 v177, v178, v179
	v_mov_b32_e32 v178, v165
	global_store_dwordx4 v[134:135], v[174:177], off offset:256
	v_pk_mul_f32 v[182:183], v[44:45], v[178:179] op_sel_hi:[1,0]
	v_pk_mul_f32 v[180:181], v[46:47], v[178:179] op_sel_hi:[1,0]
	v_pk_mul_f32 v[174:175], v[48:49], v[178:179] op_sel_hi:[1,0]
	v_pk_mul_f32 v[176:177], v[50:51], v[178:179] op_sel_hi:[1,0]
	v_lshl_add_u64 v[134:135], v[132:133], 0, s[22:23]
	v_mul_f32_e32 v214, 0xbfb8aa3b, v174
	s_mov_b64 s[22:23], 0x500000
	v_mul_f32_e32 v215, 0xbfb8aa3b, v175
	v_mul_f32_e32 v216, 0xbfb8aa3b, v176
	v_mul_f32_e32 v217, 0xbfb8aa3b, v177
	v_mul_f32_e32 v218, 0xbfb8aa3b, v182
	v_mul_f32_e32 v219, 0xbfb8aa3b, v183
	v_mul_f32_e32 v220, 0xbfb8aa3b, v180
	v_mul_f32_e32 v221, 0xbfb8aa3b, v181
	v_exp_f32_e32 v214, v214
	v_exp_f32_e32 v215, v215
	v_exp_f32_e32 v216, v216
	v_exp_f32_e32 v217, v217
	v_exp_f32_e32 v218, v218
	v_exp_f32_e32 v219, v219
	v_exp_f32_e32 v220, v220
	v_exp_f32_e32 v221, v221
	v_add_f32_e32 v214, 1.0, v214
	v_add_f32_e32 v215, 1.0, v215
	v_add_f32_e32 v216, 1.0, v216
	v_add_f32_e32 v217, 1.0, v217
	v_add_f32_e32 v218, 1.0, v218
	v_add_f32_e32 v219, 1.0, v219
	v_add_f32_e32 v220, 1.0, v220
	v_add_f32_e32 v221, 1.0, v221
	v_rcp_f32_e32 v222, v214
	v_rcp_f32_e32 v223, v215
	v_rcp_f32_e32 v224, v216
	v_rcp_f32_e32 v225, v217
	v_rcp_f32_e32 v226, v218
	v_rcp_f32_e32 v227, v219
	v_rcp_f32_e32 v228, v220
	v_rcp_f32_e32 v229, v221
	v_pk_mul_f32 v[174:175], v[174:175], v[222:223]
	v_pk_mul_f32 v[176:177], v[176:177], v[224:225]
	v_pk_mul_f32 v[180:181], v[180:181], v[228:229]
	v_cvt_pk_bf16_f32 v174, v174, v175
	v_cvt_pk_bf16_f32 v175, v176, v177
	v_pk_mul_f32 v[176:177], v[182:183], v[226:227]
	v_cvt_pk_bf16_f32 v176, v176, v177
	v_cvt_pk_bf16_f32 v177, v180, v181
	v_add_co_u32_e32 v180, vcc, s15, v132
	s_mov_b32 s15, 0x500000
	s_nop 0
	v_addc_co_u32_e32 v181, vcc, 0, v133, vcc
	global_store_dwordx4 v[180:181], v[174:177], off
	s_nop 1
	v_pk_mul_f32 v[180:181], v[38:39], v[178:179] op_sel_hi:[1,0]
	v_pk_mul_f32 v[174:175], v[40:41], v[178:179] op_sel_hi:[1,0]
	v_pk_mul_f32 v[176:177], v[42:43], v[178:179] op_sel_hi:[1,0]
	v_mul_f32_e32 v214, 0xbfb8aa3b, v174
	v_pk_mul_f32 v[178:179], v[36:37], v[178:179] op_sel_hi:[1,0]
	v_mul_f32_e32 v215, 0xbfb8aa3b, v175
	v_mul_f32_e32 v216, 0xbfb8aa3b, v176
	v_mul_f32_e32 v217, 0xbfb8aa3b, v177
	v_mul_f32_e32 v220, 0xbfb8aa3b, v180
	v_mul_f32_e32 v221, 0xbfb8aa3b, v181
	v_exp_f32_e32 v214, v214
	v_exp_f32_e32 v215, v215
	v_exp_f32_e32 v216, v216
	v_exp_f32_e32 v217, v217
	v_mul_f32_e32 v218, 0xbfb8aa3b, v178
	v_mul_f32_e32 v219, 0xbfb8aa3b, v179
	v_exp_f32_e32 v220, v220
	v_exp_f32_e32 v221, v221
	v_add_f32_e32 v214, 1.0, v214
	v_add_f32_e32 v215, 1.0, v215
	v_add_f32_e32 v216, 1.0, v216
	v_add_f32_e32 v217, 1.0, v217
	v_exp_f32_e32 v218, v218
	v_exp_f32_e32 v219, v219
	v_add_f32_e32 v220, 1.0, v220
	v_add_f32_e32 v221, 1.0, v221
	v_rcp_f32_e32 v222, v214
	v_rcp_f32_e32 v223, v215
	v_rcp_f32_e32 v224, v216
	v_rcp_f32_e32 v225, v217
	v_add_f32_e32 v218, 1.0, v218
	v_add_f32_e32 v219, 1.0, v219
	v_rcp_f32_e32 v228, v220
	v_rcp_f32_e32 v229, v221
	v_pk_mul_f32 v[174:175], v[174:175], v[222:223]
	v_pk_mul_f32 v[176:177], v[176:177], v[224:225]
	v_rcp_f32_e32 v226, v218
	v_rcp_f32_e32 v227, v219
	v_cvt_pk_bf16_f32 v174, v174, v175
	v_cvt_pk_bf16_f32 v175, v176, v177
	v_pk_mul_f32 v[176:177], v[178:179], v[226:227]
	v_cvt_pk_bf16_f32 v176, v176, v177
	v_pk_mul_f32 v[178:179], v[180:181], v[228:229]
	v_cvt_pk_bf16_f32 v177, v178, v179
	global_store_dwordx4 v[134:135], v[174:177], off offset:256
	v_pk_mul_f32 v[180:181], v[28:29], v[162:163] op_sel_hi:[1,0]
	v_pk_mul_f32 v[178:179], v[30:31], v[162:163] op_sel_hi:[1,0]
	v_pk_mul_f32 v[174:175], v[32:33], v[162:163] op_sel_hi:[1,0]
	v_pk_mul_f32 v[176:177], v[34:35], v[162:163] op_sel_hi:[1,0]
	v_lshl_add_u64 v[134:135], v[132:133], 0, s[22:23]
	v_mul_f32_e32 v214, 0xbfb8aa3b, v174
	s_mov_b64 s[22:23], 0x580000
	v_mul_f32_e32 v215, 0xbfb8aa3b, v175
	v_mul_f32_e32 v216, 0xbfb8aa3b, v176
	v_mul_f32_e32 v217, 0xbfb8aa3b, v177
	v_mul_f32_e32 v218, 0xbfb8aa3b, v180
	v_mul_f32_e32 v219, 0xbfb8aa3b, v181
	v_mul_f32_e32 v220, 0xbfb8aa3b, v178
	v_mul_f32_e32 v221, 0xbfb8aa3b, v179
	v_exp_f32_e32 v214, v214
	v_exp_f32_e32 v215, v215
	v_exp_f32_e32 v216, v216
	v_exp_f32_e32 v217, v217
	v_exp_f32_e32 v218, v218
	v_exp_f32_e32 v219, v219
	v_exp_f32_e32 v220, v220
	v_exp_f32_e32 v221, v221
	v_add_f32_e32 v214, 1.0, v214
	v_add_f32_e32 v215, 1.0, v215
	v_add_f32_e32 v216, 1.0, v216
	v_add_f32_e32 v217, 1.0, v217
	v_add_f32_e32 v218, 1.0, v218
	v_add_f32_e32 v219, 1.0, v219
	v_add_f32_e32 v220, 1.0, v220
	v_add_f32_e32 v221, 1.0, v221
	v_rcp_f32_e32 v222, v214
	v_rcp_f32_e32 v223, v215
	v_rcp_f32_e32 v224, v216
	v_rcp_f32_e32 v225, v217
	v_rcp_f32_e32 v226, v218
	v_rcp_f32_e32 v227, v219
	v_rcp_f32_e32 v228, v220
	v_rcp_f32_e32 v229, v221
	v_pk_mul_f32 v[174:175], v[174:175], v[222:223]
	v_pk_mul_f32 v[176:177], v[176:177], v[224:225]
	v_pk_mul_f32 v[178:179], v[178:179], v[228:229]
	v_cvt_pk_bf16_f32 v174, v174, v175
; __device__ __forceinline__ unsigned cvt_pk_bf16(float lo, float hi) { const f32x2 v = {lo, hi}; return __builtin_bit_cast(unsigned, __builtin_convertvector(v, bf16x2_t)); }
; __device__ __forceinline__ float sigmoidf_(float x) { return __builtin_amdgcn_rcpf(1.0f + __builtin_amdgcn_exp2f(-1.4426950408889634f * x)); }
; __device__ __forceinline__ float siluf_(float x) { return x * sigmoidf_(x); }
; template <int ACT> __device__ __forceinline__ void epi_store_bf16(const f32x4 (&acc)[2][2][4][2], const float (&rs)[2][4], bf16_t* out, int ldo, int row0, int col0) {
;     ...
;         for (int m = 0; m < 4; ++m) { bf16_t* rowp = out + (size_t)(row0 + ai * 128 + m * 16) * ldo + col0; const float s = rs[ai][m];
; #pragma unroll
;             for (int bj = 0; bj < 2; ++bj) { const f32x4 v0 = acc[ai][bj][m][0] * s, v1 = acc[ai][bj][m][1] * s;
;                 u32x4 w; w.x = cvt_pk_bf16(act_apply<ACT>(v0[0]), act_apply<ACT>(v0[1])); w.y = cvt_pk_bf16(act_apply<ACT>(v0[2]), act_apply<ACT>(v0[3]));
;                 w.z = cvt_pk_bf16(act_apply<ACT>(v1[0]), act_apply<ACT>(v1[1])); w.w = cvt_pk_bf16(act_apply<ACT>(v1[2]), act_apply<ACT>(v1[3]));
;                 *(u32x4*)(rowp + bj * 128) = w; } }
	v_cvt_pk_bf16_f32 v175, v176, v177
	v_pk_mul_f32 v[176:177], v[180:181], v[226:227]
	v_cvt_pk_bf16_f32 v176, v176, v177
	v_pk_mul_f32 v[180:181], v[20:21], v[162:163] op_sel_hi:[1,0]
	v_cvt_pk_bf16_f32 v177, v178, v179
	v_add_co_u32_e32 v178, vcc, s15, v132
	s_nop 1
	v_addc_co_u32_e32 v179, vcc, 0, v133, vcc
	global_store_dwordx4 v[178:179], v[174:177], off
	s_nop 1
	v_pk_mul_f32 v[178:179], v[22:23], v[162:163] op_sel_hi:[1,0]
	s_mov_b32 s15, 0x580000
	v_pk_mul_f32 v[174:175], v[24:25], v[162:163] op_sel_hi:[1,0]
	v_pk_mul_f32 v[176:177], v[26:27], v[162:163] op_sel_hi:[1,0]
	v_mul_f32_e32 v218, 0xbfb8aa3b, v180
	v_mul_f32_e32 v219, 0xbfb8aa3b, v181
	v_mul_f32_e32 v214, 0xbfb8aa3b, v174
	v_mul_f32_e32 v215, 0xbfb8aa3b, v175
	v_mul_f32_e32 v216, 0xbfb8aa3b, v176
	v_mul_f32_e32 v217, 0xbfb8aa3b, v177
	v_exp_f32_e32 v218, v218
	v_exp_f32_e32 v219, v219
	v_mul_f32_e32 v220, 0xbfb8aa3b, v178
	v_mul_f32_e32 v221, 0xbfb8aa3b, v179
	v_exp_f32_e32 v214, v214
	v_exp_f32_e32 v215, v215
	v_exp_f32_e32 v216, v216
	v_exp_f32_e32 v217, v217
	v_add_f32_e32 v218, 1.0, v218
	v_add_f32_e32 v219, 1.0, v219
	v_exp_f32_e32 v220, v220
	v_exp_f32_e32 v221, v221
	v_add_f32_e32 v214, 1.0, v214
	v_add_f32_e32 v215, 1.0, v215
	v_add_f32_e32 v216, 1.0, v216
	v_add_f32_e32 v217, 1.0, v217
	v_rcp_f32_e32 v226, v218
	v_rcp_f32_e32 v227, v219
	v_add_f32_e32 v220, 1.0, v220
	v_add_f32_e32 v221, 1.0, v221
	v_rcp_f32_e32 v222, v214
	v_rcp_f32_e32 v223, v215
	v_rcp_f32_e32 v224, v216
	v_rcp_f32_e32 v225, v217
	v_rcp_f32_e32 v228, v220
	v_rcp_f32_e32 v229, v221
	v_pk_mul_f32 v[174:175], v[174:175], v[222:223]
	v_pk_mul_f32 v[176:177], v[176:177], v[224:225]
	v_pk_mul_f32 v[178:179], v[178:179], v[228:229]
	v_cvt_pk_bf16_f32 v174, v174, v175
	v_cvt_pk_bf16_f32 v175, v176, v177
	v_pk_mul_f32 v[176:177], v[180:181], v[226:227]
	v_cvt_pk_bf16_f32 v176, v176, v177
	v_cvt_pk_bf16_f32 v177, v178, v179
	global_store_dwordx4 v[134:135], v[174:177], off offset:256
	s_nop 1
	v_mov_b32_e32 v134, v163
	v_lshl_add_u64 v[174:175], v[132:133], 0, s[22:23]
	v_pk_mul_f32 v[178:179], v[18:19], v[134:135] op_sel_hi:[1,0]
	v_pk_mul_f32 v[176:177], v[16:17], v[134:135] op_sel_hi:[1,0]
	v_pk_mul_f32 v[180:181], v[14:15], v[134:135] op_sel_hi:[1,0]
	v_pk_mul_f32 v[182:183], v[12:13], v[134:135] op_sel_hi:[1,0]
	v_add_co_u32_e32 v132, vcc, s15, v132
	s_mov_b64 s[22:23], 0
	v_mul_f32_e32 v214, 0xbfb8aa3b, v176
	v_mul_f32_e32 v215, 0xbfb8aa3b, v177
	v_addc_co_u32_e32 v133, vcc, 0, v133, vcc
	v_mul_f32_e32 v216, 0xbfb8aa3b, v178
	v_mul_f32_e32 v217, 0xbfb8aa3b, v179
	v_mul_f32_e32 v218, 0xbfb8aa3b, v182
	v_mul_f32_e32 v219, 0xbfb8aa3b, v183
	v_mul_f32_e32 v220, 0xbfb8aa3b, v180
	v_mul_f32_e32 v221, 0xbfb8aa3b, v181
	v_exp_f32_e32 v214, v214
	v_exp_f32_e32 v215, v215
	v_exp_f32_e32 v216, v216
	v_exp_f32_e32 v217, v217
	v_exp_f32_e32 v218, v218
	v_exp_f32_e32 v219, v219
	v_exp_f32_e32 v220, v220
	v_exp_f32_e32 v221, v221
	v_add_f32_e32 v214, 1.0, v214
	v_add_f32_e32 v215, 1.0, v215
	v_add_f32_e32 v216, 1.0, v216
	v_add_f32_e32 v217, 1.0, v217
	v_add_f32_e32 v218, 1.0, v218
	v_add_f32_e32 v219, 1.0, v219
	v_add_f32_e32 v220, 1.0, v220
	v_add_f32_e32 v221, 1.0, v221
	v_rcp_f32_e32 v222, v214
	v_rcp_f32_e32 v223, v215
	v_rcp_f32_e32 v224, v216
	v_rcp_f32_e32 v225, v217
	v_rcp_f32_e32 v226, v218
	v_rcp_f32_e32 v227, v219
	v_rcp_f32_e32 v228, v220
	v_rcp_f32_e32 v229, v221
	v_pk_mul_f32 v[176:177], v[176:177], v[222:223]
	v_pk_mul_f32 v[178:179], v[178:179], v[224:225]
	v_pk_mul_f32 v[180:181], v[180:181], v[228:229]
	v_cvt_pk_bf16_f32 v176, v176, v177
	v_cvt_pk_bf16_f32 v177, v178, v179
	v_pk_mul_f32 v[178:179], v[182:183], v[226:227]
	v_cvt_pk_bf16_f32 v178, v178, v179
	v_cvt_pk_bf16_f32 v179, v180, v181
	global_store_dwordx4 v[132:133], v[176:179], off
	v_pk_mul_f32 v[132:133], v[8:9], v[134:135] op_sel_hi:[1,0]
	s_nop 0
	v_mul_f32_e32 v169, 0xbfb8aa3b, v132
	v_exp_f32_e32 v169, v169
	v_pk_mul_f32 v[176:177], v[10:11], v[134:135] op_sel_hi:[1,0]
	v_pk_mul_f32 v[178:179], v[6:7], v[134:135] op_sel_hi:[1,0]
	v_pk_mul_f32 v[134:135], v[4:5], v[134:135] op_sel_hi:[1,0]
	v_add_f32_e32 v169, 1.0, v169
	v_rcp_f32_e32 v180, v169
	v_mul_f32_e32 v169, 0xbfb8aa3b, v133
	v_exp_f32_e32 v169, v169
	s_nop 0
	v_add_f32_e32 v169, 1.0, v169
	v_rcp_f32_e32 v181, v169
	v_mul_f32_e32 v169, 0xbfb8aa3b, v134
	v_exp_f32_e32 v169, v169
	v_pk_mul_f32 v[132:133], v[132:133], v[180:181]
	s_nop 0
	v_cvt_pk_bf16_f32 v132, v132, v133
	v_mul_f32_e32 v133, 0xbfb8aa3b, v176
	v_exp_f32_e32 v133, v133
	v_add_f32_e32 v169, 1.0, v169
	v_add_f32_e32 v133, 1.0, v133
	v_rcp_f32_e32 v180, v133
	v_mul_f32_e32 v133, 0xbfb8aa3b, v177
	v_exp_f32_e32 v133, v133
	s_nop 0
	v_add_f32_e32 v133, 1.0, v133
	v_rcp_f32_e32 v181, v133
	s_nop 0
	v_pk_mul_f32 v[176:177], v[176:177], v[180:181]
	s_nop 0
	v_cvt_pk_bf16_f32 v133, v176, v177
	v_rcp_f32_e32 v176, v169
	v_mul_f32_e32 v169, 0xbfb8aa3b, v135
	v_exp_f32_e32 v169, v169
	s_nop 0
	v_add_f32_e32 v169, 1.0, v169
	v_rcp_f32_e32 v177, v169
	s_nop 0
	v_pk_mul_f32 v[134:135], v[134:135], v[176:177]
	s_nop 0
	v_cvt_pk_bf16_f32 v134, v134, v135
	v_mul_f32_e32 v135, 0xbfb8aa3b, v178
	v_exp_f32_e32 v135, v135
	s_nop 0
	v_add_f32_e32 v135, 1.0, v135
	v_rcp_f32_e32 v176, v135
	v_mul_f32_e32 v135, 0xbfb8aa3b, v179
	v_exp_f32_e32 v135, v135
	s_nop 0
	v_add_f32_e32 v135, 1.0, v135
	v_rcp_f32_e32 v177, v135
	s_nop 0
	v_pk_mul_f32 v[192:193], v[178:179], v[176:177]
